# last layer's FFN2-down no longer writes the bf16 activation copy nothing reads (16 stores per lane skipped at step 32) + GQA add-of-zero packed adds removed
# speedup vs baseline: 1.0015x; 1.0015x over previous
; __device__ __forceinline__ unsigned pk2(float lo, float hi) { return pg8::cvt_pk_bf16(lo, hi); }
;     __device__ __forceinline__ void operator()(const pg8::f32x4 (&acc)[2][2][4][2], const pg8::Unit& u, int wr, int wc, int fr, int fq) const {
;         const int row0 = u.pm * 256 + wr * 64 + fr, col0 = u.pn * 256 + wc * 32 + 8 * fq;
; #pragma unroll
;         for (int ai = 0; ai < 2; ++ai) {
;             f32x4 bv[4][2][2];
; #pragma unroll
;             for (int m = 0; m < 4; ++m)
; #pragma unroll
;                 for (int bj = 0; bj < 2; ++bj) { const size_t off = (size_t)(row0 + ai * 128 + m * 16) * DM + col0 + bj * 128; bv[m][bj][0] = *(const f32x4*)(base + off); bv[m][bj][1] = *(const f32x4*)(base + off + 4); }
; #pragma unroll
;             for (int m = 0; m < 4; ++m) {
;                 const int row = row0 + ai * 128 + m * 16; float ss = 0.f;
; #pragma unroll
;                 for (int bj = 0; bj < 2; ++bj) {
;                     const size_t off = (size_t)row * DM + col0 + bj * 128;
;                     const f32x4 x0 = bv[m][bj][0] + acc[ai][bj][m][0] * alpha, x1 = bv[m][bj][1] + acc[ai][bj][m][1] * alpha;
;                     *(f32x4*)(out + off) = x0; *(f32x4*)(out + off + 4) = x1;
;                     u32x4 w; w.x = pk2(x0[0], x0[1]); w.y = pk2(x0[2], x0[3]); w.z = pk2(x1[0], x1[1]); w.w = pk2(x1[2], x1[3]);
;                     *(u32x4*)(xb + off) = w;
;                     ss += ((x0[0] * x0[0] + x0[1] * x0[1]) + (x0[2] * x0[2] + x0[3] * x0[3])) + ((x1[0] * x1[0] + x1[1] * x1[1]) + (x1[2] * x1[2] + x1[3] * x1[3]));
;                 }
;                 ss += __shfl_xor(ss, 16); ss += __shfl_xor(ss, 32);
;                 if (ssq && fq == 0) ssq[(size_t)row * 16 + u.pn * 4 + wc] = ss;
.LBB0_592:
	v_xor_b32_e32 v132, 16, v233
	v_cmp_lt_i32_e32 vcc, v132, v234
	v_lshl_add_u32 v208, s59, 8, v35
	v_lshl_or_b32 v206, s8, 8, v219
	v_cndmask_b32_e32 v132, v233, v132, vcc
	v_lshlrev_b32_e32 v222, 2, v132
	v_xor_b32_e32 v132, 32, v233
	v_cmp_lt_i32_e32 vcc, v132, v234
	v_ashrrev_i32_e32 v207, 31, v206
	v_ashrrev_i32_e32 v209, 31, v208
	v_cndmask_b32_e32 v132, v233, v132, vcc
	v_lshlrev_b32_e32 v221, 2, v132
	v_lshl_add_u64 v[210:211], v[206:207], 2, s[12:13]
	v_lshlrev_b64 v[132:133], 12, v[208:209]
	v_lshl_add_u64 v[132:133], v[210:211], 0, v[132:133]
	global_load_dwordx4 v[224:227], v[132:133], off offset:16
	global_load_dwordx4 v[248:251], v[132:133], off
	global_load_dwordx4 v[180:183], v[132:133], off offset:528
	global_load_dwordx4 v[184:187], v[132:133], off offset:512
	v_or_b32_e32 v216, 16, v208
	v_ashrrev_i32_e32 v217, 31, v216
	v_lshlrev_b64 v[132:133], 12, v[216:217]
	v_or_b32_e32 v214, 32, v208
	v_lshl_add_u64 v[132:133], v[210:211], 0, v[132:133]
	v_ashrrev_i32_e32 v215, 31, v214
	global_load_dwordx4 v[172:175], v[132:133], off offset:16
	global_load_dwordx4 v[176:179], v[132:133], off
	global_load_dwordx4 v[164:167], v[132:133], off offset:528
	global_load_dwordx4 v[168:171], v[132:133], off offset:512
	v_lshlrev_b64 v[132:133], 12, v[214:215]
	v_or_b32_e32 v212, 48, v208
	v_lshl_add_u64 v[132:133], v[210:211], 0, v[132:133]
	v_ashrrev_i32_e32 v213, 31, v212
	global_load_dwordx4 v[156:159], v[132:133], off offset:16
	global_load_dwordx4 v[160:163], v[132:133], off
	global_load_dwordx4 v[140:143], v[132:133], off offset:528
	global_load_dwordx4 v[148:151], v[132:133], off offset:512
	v_lshlrev_b64 v[132:133], 12, v[212:213]
	v_lshl_add_u64 v[136:137], v[210:211], 0, v[132:133]
	global_load_dwordx4 v[144:147], v[136:137], off offset:16
	global_load_dwordx4 v[152:155], v[136:137], off
	global_load_dwordx4 v[132:135], v[136:137], off offset:528
	s_nop 0
	global_load_dwordx4 v[136:139], v[136:137], off offset:512
	v_lshlrev_b64 v[236:237], 10, v[208:209]
	v_lshl_add_u64 v[236:237], v[236:237], 0, v[206:207]
	v_mov_b32_e32 v193, v192
	v_lshl_add_u64 v[238:239], v[236:237], 2, s[24:25]
	v_lshlrev_b64 v[236:237], 1, v[236:237]
	v_lshl_add_u64 v[240:241], s[2:3], 0, v[236:237]
	s_lshl_b32 s22, s8, 2
	v_or_b32_e32 v236, 0x100, v236
	s_ashr_i32 s23, s22, 31
	s_waitcnt vmcnt(0)
	v_pk_fma_f32 v[124:125], v[194:195], v[124:125], v[224:225]
	v_pk_fma_f32 v[130:131], v[192:193], v[130:131], v[250:251]
	v_pk_fma_f32 v[128:129], v[194:195], v[128:129], v[248:249]
	v_pk_fma_f32 v[126:127], v[192:193], v[126:127], v[226:227]
	global_store_dwordx4 v[238:239], v[128:131], off
	global_store_dwordx4 v[238:239], v[124:127], off offset:16
	v_cvt_pk_bf16_f32 v224, v128, v129
	v_cvt_pk_bf16_f32 v226, v124, v125
	v_mul_f32_e32 v129, v129, v129
	v_mul_f32_e32 v125, v125, v125
	v_fmac_f32_e32 v129, v128, v128
	v_mul_f32_e32 v128, v131, v131
	v_fmac_f32_e32 v125, v124, v124
	v_mul_f32_e32 v124, v127, v127
	v_fmac_f32_e32 v128, v130, v130
	v_fmac_f32_e32 v124, v126, v126
	v_cvt_pk_bf16_f32 v225, v130, v131
	v_cvt_pk_bf16_f32 v227, v126, v127
	v_add_f32_e32 v128, v129, v128
	v_add_f32_e32 v124, v125, v124
	v_pk_fma_f32 v[122:123], v[192:193], v[122:123], v[186:187]
	v_pk_fma_f32 v[120:121], v[194:195], v[120:121], v[184:185]
	v_pk_fma_f32 v[116:117], v[194:195], v[116:117], v[180:181]
	s_cmp_eq_u32 s28, 32
	s_cbranch_scc1 .Lxbskip_15
	global_store_dwordx4 v[240:241], v[224:227], off
.Lxbskip_15:
	v_add_f32_e32 v130, v128, v124
	v_pk_fma_f32 v[118:119], v[192:193], v[118:119], v[182:183]
	global_store_dwordx4 v[238:239], v[120:123], off offset:512
	global_store_dwordx4 v[238:239], v[116:119], off offset:528
	v_cvt_pk_bf16_f32 v124, v120, v121
	v_cvt_pk_bf16_f32 v126, v116, v117
	v_mul_f32_e32 v121, v121, v121
	v_mul_f32_e32 v117, v117, v117
	v_fmac_f32_e32 v121, v120, v120
	v_mul_f32_e32 v120, v123, v123
	v_fmac_f32_e32 v117, v116, v116
	v_mul_f32_e32 v116, v119, v119
	v_fmac_f32_e32 v120, v122, v122
	v_fmac_f32_e32 v116, v118, v118
	v_add_f32_e32 v120, v121, v120
	v_add_f32_e32 v116, v117, v116
	v_add_f32_e32 v116, v120, v116
	v_add_f32_e32 v116, v130, v116
	ds_bpermute_b32 v117, v222, v116
	v_cvt_pk_bf16_f32 v125, v122, v123
	v_cvt_pk_bf16_f32 v127, v118, v119
	v_lshl_add_u64 v[128:129], s[2:3], 0, v[236:237]
	s_cmp_eq_u32 s28, 32
	s_cbranch_scc1 .Lxbskip_14
	global_store_dwordx4 v[128:129], v[124:127], off
.Lxbskip_14:
	s_waitcnt lgkmcnt(0)
	v_add_f32_e32 v116, v116, v117
	ds_bpermute_b32 v117, v221, v116
	s_and_saveexec_b64 s[40:41], s[18:19]
	s_cbranch_execz .LBB0_594
	s_waitcnt lgkmcnt(0)
	v_add_f32_e32 v118, v116, v117
	v_lshlrev_b64 v[116:117], 6, v[208:209]
	v_lshl_add_u64 v[116:117], s[14:15], 0, v[116:117]
	v_lshl_add_u64 v[116:117], s[22:23], 2, v[116:117]
	s_lshl_b32 s8, s54, 2
	v_lshl_add_u64 v[116:117], v[116:117], 0, s[8:9]
	global_store_dword v[116:117], v118, off
; __device__ __forceinline__ unsigned pk2(float lo, float hi) { return pg8::cvt_pk_bf16(lo, hi); }
;     __device__ __forceinline__ void operator()(const pg8::f32x4 (&acc)[2][2][4][2], const pg8::Unit& u, int wr, int wc, int fr, int fq) const {
;     ...
;                 for (int bj = 0; bj < 2; ++bj) { const size_t off = (size_t)(row0 + ai * 128 + m * 16) * DM + col0 + bj * 128; bv[m][bj][0] = *(const f32x4*)(base + off); bv[m][bj][1] = *(const f32x4*)(base + off + 4); }
; #pragma unroll
;             for (int m = 0; m < 4; ++m) {
;                 const int row = row0 + ai * 128 + m * 16; float ss = 0.f;
; #pragma unroll
;                 for (int bj = 0; bj < 2; ++bj) {
;                     const size_t off = (size_t)row * DM + col0 + bj * 128;
;                     const f32x4 x0 = bv[m][bj][0] + acc[ai][bj][m][0] * alpha, x1 = bv[m][bj][1] + acc[ai][bj][m][1] * alpha;
;                     *(f32x4*)(out + off) = x0; *(f32x4*)(out + off + 4) = x1;
;                     u32x4 w; w.x = pk2(x0[0], x0[1]); w.y = pk2(x0[2], x0[3]); w.z = pk2(x1[0], x1[1]); w.w = pk2(x1[2], x1[3]);
;                     *(u32x4*)(xb + off) = w;
;                     ss += ((x0[0] * x0[0] + x0[1] * x0[1]) + (x0[2] * x0[2] + x0[3] * x0[3])) + ((x1[0] * x1[0] + x1[1] * x1[1]) + (x1[2] * x1[2] + x1[3] * x1[3]));
;                 }
;                 ss += __shfl_xor(ss, 16); ss += __shfl_xor(ss, 32);
;                 if (ssq && fq == 0) ssq[(size_t)row * 16 + u.pn * 4 + wc] = ss;
;             }
.LBB0_594:
	s_or_b64 exec, exec, s[40:41]
	s_waitcnt lgkmcnt(0)
	v_lshlrev_b64 v[116:117], 10, v[216:217]
	v_lshl_add_u64 v[120:121], v[116:117], 0, v[206:207]
	v_pk_fma_f32 v[114:115], v[192:193], v[114:115], v[178:179]
	v_pk_fma_f32 v[112:113], v[194:195], v[112:113], v[176:177]
	v_pk_fma_f32 v[108:109], v[194:195], v[108:109], v[172:173]
	v_lshl_add_u64 v[122:123], v[120:121], 2, s[24:25]
	v_pk_fma_f32 v[110:111], v[192:193], v[110:111], v[174:175]
	global_store_dwordx4 v[122:123], v[112:115], off
	global_store_dwordx4 v[122:123], v[108:111], off offset:16
	v_cvt_pk_bf16_f32 v118, v108, v109
	v_pk_fma_f32 v[106:107], v[192:193], v[106:107], v[170:171]
	v_mul_f32_e32 v109, v109, v109
	v_fmac_f32_e32 v109, v108, v108
	v_mul_f32_e32 v108, v111, v111
	v_fmac_f32_e32 v108, v110, v110
	v_pk_fma_f32 v[104:105], v[194:195], v[104:105], v[168:169]
	v_cvt_pk_bf16_f32 v119, v110, v111
	v_add_f32_e32 v108, v109, v108
	v_mul_f32_e32 v109, v105, v105
	v_mul_f32_e32 v110, v107, v107
	v_cvt_pk_bf16_f32 v116, v112, v113
	v_mul_f32_e32 v113, v113, v113
	v_pk_fma_f32 v[102:103], v[192:193], v[102:103], v[166:167]
	v_pk_fma_f32 v[100:101], v[194:195], v[100:101], v[164:165]
	v_fmac_f32_e32 v109, v104, v104
	v_fmac_f32_e32 v110, v106, v106
	v_fmac_f32_e32 v113, v112, v112
	v_mul_f32_e32 v112, v115, v115
	v_add_f32_e32 v109, v109, v110
	v_mul_f32_e32 v110, v101, v101
	v_mul_f32_e32 v111, v103, v103
	v_fmac_f32_e32 v112, v114, v114
	v_fmac_f32_e32 v110, v100, v100
	v_fmac_f32_e32 v111, v102, v102
	v_add_f32_e32 v112, v113, v112
	v_add_f32_e32 v110, v110, v111
	v_add_f32_e32 v108, v112, v108
	v_add_f32_e32 v109, v109, v110
	v_add_f32_e32 v108, v108, v109
	ds_bpermute_b32 v109, v222, v108
	v_lshlrev_b64 v[120:121], 1, v[120:121]
	v_cvt_pk_bf16_f32 v117, v114, v115
	v_lshl_add_u64 v[124:125], s[2:3], 0, v[120:121]
	s_cmp_eq_u32 s28, 32
	s_cbranch_scc1 .Lxbskip_13
	global_store_dwordx4 v[124:125], v[116:119], off
.Lxbskip_13:
	global_store_dwordx4 v[122:123], v[104:107], off offset:512
	global_store_dwordx4 v[122:123], v[100:103], off offset:528
	v_or_b32_e32 v120, 0x100, v120
	v_cvt_pk_bf16_f32 v104, v104, v105
	v_cvt_pk_bf16_f32 v105, v106, v107
	v_cvt_pk_bf16_f32 v106, v100, v101
	s_waitcnt lgkmcnt(0)
	v_add_f32_e32 v100, v108, v109
	ds_bpermute_b32 v101, v221, v100
	v_cvt_pk_bf16_f32 v107, v102, v103
	v_lshl_add_u64 v[102:103], s[2:3], 0, v[120:121]
	s_cmp_eq_u32 s28, 32
	s_cbranch_scc1 .Lxbskip_12
	global_store_dwordx4 v[102:103], v[104:107], off
.Lxbskip_12:
	s_and_saveexec_b64 s[40:41], s[18:19]
	s_cbranch_execz .LBB0_596
	s_waitcnt lgkmcnt(0)
	v_add_f32_e32 v102, v100, v101
	v_lshlrev_b64 v[100:101], 6, v[216:217]
	v_lshl_add_u64 v[100:101], s[14:15], 0, v[100:101]
	v_lshl_add_u64 v[100:101], s[22:23], 2, v[100:101]
	s_lshl_b32 s8, s54, 2
	v_lshl_add_u64 v[100:101], v[100:101], 0, s[8:9]
	global_store_dword v[100:101], v102, off
.LBB0_596:
	s_or_b64 exec, exec, s[40:41]
	s_waitcnt lgkmcnt(0)
	v_lshlrev_b64 v[100:101], 10, v[214:215]
	v_lshl_add_u64 v[104:105], v[100:101], 0, v[206:207]
	v_mov_b32_e32 v193, v192
	v_pk_fma_f32 v[98:99], v[192:193], v[98:99], v[162:163]
	v_pk_fma_f32 v[96:97], v[194:195], v[96:97], v[160:161]
	v_pk_fma_f32 v[92:93], v[194:195], v[92:93], v[156:157]
	v_lshl_add_u64 v[106:107], v[104:105], 2, s[24:25]
	v_pk_fma_f32 v[94:95], v[192:193], v[94:95], v[158:159]
	global_store_dwordx4 v[106:107], v[96:99], off
	global_store_dwordx4 v[106:107], v[92:95], off offset:16
	v_cvt_pk_bf16_f32 v102, v92, v93
	v_pk_fma_f32 v[90:91], v[192:193], v[90:91], v[150:151]
	v_mul_f32_e32 v93, v93, v93
	v_fmac_f32_e32 v93, v92, v92
	v_mul_f32_e32 v92, v95, v95
	v_fmac_f32_e32 v92, v94, v94
	v_pk_fma_f32 v[88:89], v[194:195], v[88:89], v[148:149]
	v_cvt_pk_bf16_f32 v103, v94, v95
	v_add_f32_e32 v92, v93, v92
	v_mul_f32_e32 v93, v89, v89
	v_mul_f32_e32 v94, v91, v91
	v_cvt_pk_bf16_f32 v100, v96, v97
	v_mul_f32_e32 v97, v97, v97
	v_pk_fma_f32 v[86:87], v[192:193], v[86:87], v[142:143]
	v_pk_fma_f32 v[84:85], v[194:195], v[84:85], v[140:141]
	v_fmac_f32_e32 v93, v88, v88
	v_fmac_f32_e32 v94, v90, v90
	v_fmac_f32_e32 v97, v96, v96
	v_mul_f32_e32 v96, v99, v99
	v_add_f32_e32 v93, v93, v94
	v_mul_f32_e32 v94, v85, v85
	v_mul_f32_e32 v95, v87, v87
	v_fmac_f32_e32 v96, v98, v98
	v_fmac_f32_e32 v94, v84, v84
	v_fmac_f32_e32 v95, v86, v86
	v_add_f32_e32 v96, v97, v96
	v_add_f32_e32 v94, v94, v95
	v_add_f32_e32 v92, v96, v92
	v_add_f32_e32 v93, v93, v94
	v_add_f32_e32 v92, v92, v93
	ds_bpermute_b32 v93, v222, v92
	v_lshlrev_b64 v[104:105], 1, v[104:105]
	v_cvt_pk_bf16_f32 v101, v98, v99
	v_lshl_add_u64 v[108:109], s[2:3], 0, v[104:105]
	s_cmp_eq_u32 s28, 32
	s_cbranch_scc1 .Lxbskip_11
	global_store_dwordx4 v[108:109], v[100:103], off
.Lxbskip_11:
	global_store_dwordx4 v[106:107], v[88:91], off offset:512
	global_store_dwordx4 v[106:107], v[84:87], off offset:528
	v_or_b32_e32 v104, 0x100, v104
	v_cvt_pk_bf16_f32 v88, v88, v89
	v_cvt_pk_bf16_f32 v89, v90, v91
	v_cvt_pk_bf16_f32 v90, v84, v85
	s_waitcnt lgkmcnt(0)
	v_add_f32_e32 v84, v92, v93
	ds_bpermute_b32 v85, v221, v84
	v_cvt_pk_bf16_f32 v91, v86, v87
	v_lshl_add_u64 v[86:87], s[2:3], 0, v[104:105]
	s_cmp_eq_u32 s28, 32
	s_cbranch_scc1 .Lxbskip_10
	global_store_dwordx4 v[86:87], v[88:91], off
.Lxbskip_10:
	s_and_saveexec_b64 s[40:41], s[18:19]
	s_cbranch_execz .LBB0_598
	s_waitcnt lgkmcnt(0)
	v_add_f32_e32 v86, v84, v85
	v_lshlrev_b64 v[84:85], 6, v[214:215]
	v_lshl_add_u64 v[84:85], s[14:15], 0, v[84:85]
	v_lshl_add_u64 v[84:85], s[22:23], 2, v[84:85]
	s_lshl_b32 s8, s54, 2
	v_lshl_add_u64 v[84:85], v[84:85], 0, s[8:9]
	global_store_dword v[84:85], v86, off
; __device__ __forceinline__ unsigned pk2(float lo, float hi) { return pg8::cvt_pk_bf16(lo, hi); }
;     __device__ __forceinline__ void operator()(const pg8::f32x4 (&acc)[2][2][4][2], const pg8::Unit& u, int wr, int wc, int fr, int fq) const {
;     ...
;                 for (int bj = 0; bj < 2; ++bj) { const size_t off = (size_t)(row0 + ai * 128 + m * 16) * DM + col0 + bj * 128; bv[m][bj][0] = *(const f32x4*)(base + off); bv[m][bj][1] = *(const f32x4*)(base + off + 4); }
; #pragma unroll
;             for (int m = 0; m < 4; ++m) {
;                 const int row = row0 + ai * 128 + m * 16; float ss = 0.f;
; #pragma unroll
;                 for (int bj = 0; bj < 2; ++bj) {
;                     const size_t off = (size_t)row * DM + col0 + bj * 128;
;                     const f32x4 x0 = bv[m][bj][0] + acc[ai][bj][m][0] * alpha, x1 = bv[m][bj][1] + acc[ai][bj][m][1] * alpha;
;                     *(f32x4*)(out + off) = x0; *(f32x4*)(out + off + 4) = x1;
;                     u32x4 w; w.x = pk2(x0[0], x0[1]); w.y = pk2(x0[2], x0[3]); w.z = pk2(x1[0], x1[1]); w.w = pk2(x1[2], x1[3]);
;                     *(u32x4*)(xb + off) = w;
;                     ss += ((x0[0] * x0[0] + x0[1] * x0[1]) + (x0[2] * x0[2] + x0[3] * x0[3])) + ((x1[0] * x1[0] + x1[1] * x1[1]) + (x1[2] * x1[2] + x1[3] * x1[3]));
;                 }
;                 ss += __shfl_xor(ss, 16); ss += __shfl_xor(ss, 32);
;                 if (ssq && fq == 0) ssq[(size_t)row * 16 + u.pn * 4 + wc] = ss;
;             }
.LBB0_598:
	s_or_b64 exec, exec, s[40:41]
	s_waitcnt lgkmcnt(0)
	v_lshlrev_b64 v[84:85], 10, v[212:213]
	v_lshl_add_u64 v[88:89], v[84:85], 0, v[206:207]
	v_pk_fma_f32 v[82:83], v[192:193], v[82:83], v[154:155]
	v_pk_fma_f32 v[80:81], v[194:195], v[80:81], v[152:153]
	v_pk_fma_f32 v[76:77], v[194:195], v[76:77], v[144:145]
	v_lshl_add_u64 v[90:91], v[88:89], 2, s[24:25]
	v_pk_fma_f32 v[78:79], v[192:193], v[78:79], v[146:147]
	global_store_dwordx4 v[90:91], v[80:83], off
	global_store_dwordx4 v[90:91], v[76:79], off offset:16
	v_cvt_pk_bf16_f32 v86, v76, v77
	v_pk_fma_f32 v[74:75], v[192:193], v[74:75], v[138:139]
	v_mul_f32_e32 v77, v77, v77
	v_fmac_f32_e32 v77, v76, v76
	v_mul_f32_e32 v76, v79, v79
	v_fmac_f32_e32 v76, v78, v78
	v_pk_fma_f32 v[72:73], v[194:195], v[72:73], v[136:137]
	v_cvt_pk_bf16_f32 v87, v78, v79
	v_add_f32_e32 v76, v77, v76
	v_mul_f32_e32 v77, v73, v73
	v_mul_f32_e32 v78, v75, v75
	v_cvt_pk_bf16_f32 v84, v80, v81
	v_mul_f32_e32 v81, v81, v81
	v_pk_fma_f32 v[70:71], v[192:193], v[70:71], v[134:135]
	v_pk_fma_f32 v[68:69], v[194:195], v[68:69], v[132:133]
	v_fmac_f32_e32 v77, v72, v72
	v_fmac_f32_e32 v78, v74, v74
	v_fmac_f32_e32 v81, v80, v80
	v_mul_f32_e32 v80, v83, v83
	v_add_f32_e32 v77, v77, v78
	v_mul_f32_e32 v78, v69, v69
	v_mul_f32_e32 v79, v71, v71
	v_fmac_f32_e32 v80, v82, v82
	v_fmac_f32_e32 v78, v68, v68
	v_fmac_f32_e32 v79, v70, v70
	v_add_f32_e32 v80, v81, v80
	v_add_f32_e32 v78, v78, v79
	v_add_f32_e32 v76, v80, v76
	v_add_f32_e32 v77, v77, v78
	v_add_f32_e32 v76, v76, v77
	ds_bpermute_b32 v77, v222, v76
	v_lshlrev_b64 v[88:89], 1, v[88:89]
	v_cvt_pk_bf16_f32 v85, v82, v83
	v_lshl_add_u64 v[92:93], s[2:3], 0, v[88:89]
	s_cmp_eq_u32 s28, 32
	s_cbranch_scc1 .Lxbskip_9
	global_store_dwordx4 v[92:93], v[84:87], off
.Lxbskip_9:
	global_store_dwordx4 v[90:91], v[72:75], off offset:512
	global_store_dwordx4 v[90:91], v[68:71], off offset:528
	v_or_b32_e32 v88, 0x100, v88
	v_cvt_pk_bf16_f32 v72, v72, v73
	v_cvt_pk_bf16_f32 v73, v74, v75
	v_cvt_pk_bf16_f32 v74, v68, v69
	s_waitcnt lgkmcnt(0)
	v_add_f32_e32 v68, v76, v77
	ds_bpermute_b32 v69, v221, v68
	v_cvt_pk_bf16_f32 v75, v70, v71
	v_lshl_add_u64 v[70:71], s[2:3], 0, v[88:89]
	s_cmp_eq_u32 s28, 32
	s_cbranch_scc1 .Lxbskip_8
	global_store_dwordx4 v[70:71], v[72:75], off
.Lxbskip_8:
	s_and_saveexec_b64 s[40:41], s[18:19]
	s_cbranch_execz .LBB0_600
	s_waitcnt lgkmcnt(0)
	v_add_f32_e32 v70, v68, v69
	v_lshlrev_b64 v[68:69], 6, v[212:213]
	v_lshl_add_u64 v[68:69], s[14:15], 0, v[68:69]
	v_lshl_add_u64 v[68:69], s[22:23], 2, v[68:69]
	s_lshl_b32 s8, s54, 2
	v_lshl_add_u64 v[68:69], v[68:69], 0, s[8:9]
	global_store_dword v[68:69], v70, off
.LBB0_600:
	s_or_b64 exec, exec, s[40:41]
	v_add_u32_e32 v130, 0x80, v208
	v_ashrrev_i32_e32 v131, 31, v130
	s_waitcnt lgkmcnt(0)
	v_lshlrev_b64 v[68:69], 12, v[130:131]
	v_lshl_add_u64 v[68:69], v[210:211], 0, v[68:69]
	global_load_dwordx4 v[132:135], v[68:69], off offset:16
	global_load_dwordx4 v[136:139], v[68:69], off
	global_load_dwordx4 v[116:119], v[68:69], off offset:528
	global_load_dwordx4 v[120:123], v[68:69], off offset:512
	v_add_u32_e32 v128, 0x90, v208
	v_ashrrev_i32_e32 v129, 31, v128
	v_lshlrev_b64 v[68:69], 12, v[128:129]
	v_add_u32_e32 v126, 0xa0, v208
	v_lshl_add_u64 v[68:69], v[210:211], 0, v[68:69]
	v_ashrrev_i32_e32 v127, 31, v126
	global_load_dwordx4 v[108:111], v[68:69], off offset:16
	global_load_dwordx4 v[112:115], v[68:69], off
	global_load_dwordx4 v[100:103], v[68:69], off offset:528
	global_load_dwordx4 v[104:107], v[68:69], off offset:512
	v_lshlrev_b64 v[68:69], 12, v[126:127]
	v_add_u32_e32 v124, 0xb0, v208
	v_lshl_add_u64 v[68:69], v[210:211], 0, v[68:69]
	v_ashrrev_i32_e32 v125, 31, v124
	global_load_dwordx4 v[92:95], v[68:69], off offset:16
	global_load_dwordx4 v[96:99], v[68:69], off
	global_load_dwordx4 v[76:79], v[68:69], off offset:528
	global_load_dwordx4 v[84:87], v[68:69], off offset:512
	v_lshlrev_b64 v[68:69], 12, v[124:125]
	v_lshl_add_u64 v[72:73], v[210:211], 0, v[68:69]
	global_load_dwordx4 v[80:83], v[72:73], off offset:16
	global_load_dwordx4 v[88:91], v[72:73], off
	global_load_dwordx4 v[68:71], v[72:73], off offset:528
	s_nop 0
	global_load_dwordx4 v[72:75], v[72:73], off offset:512
	v_lshlrev_b64 v[140:141], 10, v[130:131]
	v_lshl_add_u64 v[140:141], v[140:141], 0, v[206:207]
	v_mov_b32_e32 v193, v192
	s_waitcnt vmcnt(15)
	v_pk_fma_f32 v[60:61], v[194:195], v[60:61], v[132:133]
	s_waitcnt vmcnt(14)
	v_pk_fma_f32 v[66:67], v[192:193], v[66:67], v[138:139]
	v_pk_fma_f32 v[64:65], v[194:195], v[64:65], v[136:137]
	v_lshl_add_u64 v[136:137], v[140:141], 2, s[24:25]
	v_pk_fma_f32 v[62:63], v[192:193], v[62:63], v[134:135]
	global_store_dwordx4 v[136:137], v[64:67], off
	global_store_dwordx4 v[136:137], v[60:63], off offset:16
	v_cvt_pk_bf16_f32 v132, v64, v65
	v_cvt_pk_bf16_f32 v134, v60, v61
	v_mul_f32_e32 v65, v65, v65
	v_mul_f32_e32 v61, v61, v61
	v_fmac_f32_e32 v65, v64, v64
	v_mul_f32_e32 v64, v67, v67
	v_fmac_f32_e32 v61, v60, v60
	v_mul_f32_e32 v60, v63, v63
	v_lshlrev_b64 v[138:139], 1, v[140:141]
	v_fmac_f32_e32 v64, v66, v66
	v_fmac_f32_e32 v60, v62, v62
	v_cvt_pk_bf16_f32 v133, v66, v67
	v_cvt_pk_bf16_f32 v135, v62, v63
	v_lshl_add_u64 v[140:141], s[2:3], 0, v[138:139]
	v_add_f32_e32 v64, v65, v64
	v_add_f32_e32 v60, v61, v60
	s_waitcnt vmcnt(14)
	v_pk_fma_f32 v[58:59], v[192:193], v[58:59], v[122:123]
	v_pk_fma_f32 v[56:57], v[194:195], v[56:57], v[120:121]
	v_pk_fma_f32 v[52:53], v[194:195], v[52:53], v[116:117]
	s_cmp_eq_u32 s28, 32
	s_cbranch_scc1 .Lxbskip_7
	global_store_dwordx4 v[140:141], v[132:135], off
; __device__ __forceinline__ unsigned pk2(float lo, float hi) { return pg8::cvt_pk_bf16(lo, hi); }
;     __device__ __forceinline__ void operator()(const pg8::f32x4 (&acc)[2][2][4][2], const pg8::Unit& u, int wr, int wc, int fr, int fq) const {
;     ...
;                 for (int bj = 0; bj < 2; ++bj) { const size_t off = (size_t)(row0 + ai * 128 + m * 16) * DM + col0 + bj * 128; bv[m][bj][0] = *(const f32x4*)(base + off); bv[m][bj][1] = *(const f32x4*)(base + off + 4); }
; #pragma unroll
;             for (int m = 0; m < 4; ++m) {
;                 const int row = row0 + ai * 128 + m * 16; float ss = 0.f;
; #pragma unroll
;                 for (int bj = 0; bj < 2; ++bj) {
;                     const size_t off = (size_t)row * DM + col0 + bj * 128;
;                     const f32x4 x0 = bv[m][bj][0] + acc[ai][bj][m][0] * alpha, x1 = bv[m][bj][1] + acc[ai][bj][m][1] * alpha;
;                     *(f32x4*)(out + off) = x0; *(f32x4*)(out + off + 4) = x1;
;                     u32x4 w; w.x = pk2(x0[0], x0[1]); w.y = pk2(x0[2], x0[3]); w.z = pk2(x1[0], x1[1]); w.w = pk2(x1[2], x1[3]);
;                     *(u32x4*)(xb + off) = w;
;                     ss += ((x0[0] * x0[0] + x0[1] * x0[1]) + (x0[2] * x0[2] + x0[3] * x0[3])) + ((x1[0] * x1[0] + x1[1] * x1[1]) + (x1[2] * x1[2] + x1[3] * x1[3]));
;                 }
;                 ss += __shfl_xor(ss, 16); ss += __shfl_xor(ss, 32);
;                 if (ssq && fq == 0) ssq[(size_t)row * 16 + u.pn * 4 + wc] = ss;
;             }
.Lxbskip_7:
	v_add_f32_e32 v66, v64, v60
	v_pk_fma_f32 v[54:55], v[192:193], v[54:55], v[118:119]
	global_store_dwordx4 v[136:137], v[56:59], off offset:512
	global_store_dwordx4 v[136:137], v[52:55], off offset:528
	v_cvt_pk_bf16_f32 v60, v56, v57
	v_cvt_pk_bf16_f32 v62, v52, v53
	v_mul_f32_e32 v57, v57, v57
	v_mul_f32_e32 v53, v53, v53
	v_fmac_f32_e32 v57, v56, v56
	v_mul_f32_e32 v56, v59, v59
	v_fmac_f32_e32 v53, v52, v52
	v_mul_f32_e32 v52, v55, v55
	v_fmac_f32_e32 v56, v58, v58
	v_fmac_f32_e32 v52, v54, v54
	v_add_f32_e32 v56, v57, v56
	v_add_f32_e32 v52, v53, v52
	v_add_f32_e32 v52, v56, v52
	v_add_f32_e32 v52, v66, v52
	ds_bpermute_b32 v53, v222, v52
	v_or_b32_e32 v138, 0x100, v138
	v_cvt_pk_bf16_f32 v61, v58, v59
	v_cvt_pk_bf16_f32 v63, v54, v55
	v_lshl_add_u64 v[64:65], s[2:3], 0, v[138:139]
	s_waitcnt lgkmcnt(0)
	v_add_f32_e32 v52, v52, v53
	ds_bpermute_b32 v53, v221, v52
	s_cmp_eq_u32 s28, 32
	s_cbranch_scc1 .Lxbskip_6
	global_store_dwordx4 v[64:65], v[60:63], off
.Lxbskip_6:
	s_and_saveexec_b64 s[40:41], s[18:19]
	s_cbranch_execz .LBB0_602
	s_waitcnt lgkmcnt(0)
	v_add_f32_e32 v54, v52, v53
	v_lshlrev_b64 v[52:53], 6, v[130:131]
	v_lshl_add_u64 v[52:53], s[14:15], 0, v[52:53]
	v_lshl_add_u64 v[52:53], s[22:23], 2, v[52:53]
	s_lshl_b32 s8, s54, 2
	v_lshl_add_u64 v[52:53], v[52:53], 0, s[8:9]
	global_store_dword v[52:53], v54, off
.LBB0_602:
	s_or_b64 exec, exec, s[40:41]
	s_waitcnt lgkmcnt(0)
	v_lshlrev_b64 v[52:53], 10, v[128:129]
	v_lshl_add_u64 v[56:57], v[52:53], 0, v[206:207]
	s_waitcnt vmcnt(16)
	v_pk_fma_f32 v[50:51], v[192:193], v[50:51], v[114:115]
	v_pk_fma_f32 v[48:49], v[194:195], v[48:49], v[112:113]
	v_pk_fma_f32 v[44:45], v[194:195], v[44:45], v[108:109]
	v_lshl_add_u64 v[58:59], v[56:57], 2, s[24:25]
	v_pk_fma_f32 v[46:47], v[192:193], v[46:47], v[110:111]
	global_store_dwordx4 v[58:59], v[48:51], off
	global_store_dwordx4 v[58:59], v[44:47], off offset:16
	v_cvt_pk_bf16_f32 v54, v44, v45
	s_waitcnt vmcnt(16)
	v_pk_fma_f32 v[42:43], v[192:193], v[42:43], v[106:107]
	v_mul_f32_e32 v45, v45, v45
	v_fmac_f32_e32 v45, v44, v44
	v_mul_f32_e32 v44, v47, v47
	v_fmac_f32_e32 v44, v46, v46
	v_pk_fma_f32 v[40:41], v[194:195], v[40:41], v[104:105]
	v_cvt_pk_bf16_f32 v55, v46, v47
	v_add_f32_e32 v44, v45, v44
	v_mul_f32_e32 v45, v41, v41
	v_mul_f32_e32 v46, v43, v43
	v_cvt_pk_bf16_f32 v52, v48, v49
	v_mul_f32_e32 v49, v49, v49
	v_pk_fma_f32 v[38:39], v[192:193], v[38:39], v[102:103]
	v_pk_fma_f32 v[36:37], v[194:195], v[36:37], v[100:101]
	v_fmac_f32_e32 v45, v40, v40
	v_fmac_f32_e32 v46, v42, v42
	v_fmac_f32_e32 v49, v48, v48
	v_mul_f32_e32 v48, v51, v51
	v_add_f32_e32 v45, v45, v46
	v_mul_f32_e32 v46, v37, v37
	v_mul_f32_e32 v47, v39, v39
	v_fmac_f32_e32 v48, v50, v50
	v_fmac_f32_e32 v46, v36, v36
	v_fmac_f32_e32 v47, v38, v38
	v_add_f32_e32 v48, v49, v48
	v_add_f32_e32 v46, v46, v47
	v_add_f32_e32 v44, v48, v44
	v_add_f32_e32 v45, v45, v46
	v_add_f32_e32 v44, v44, v45
	ds_bpermute_b32 v45, v222, v44
	v_lshlrev_b64 v[56:57], 1, v[56:57]
	v_cvt_pk_bf16_f32 v53, v50, v51
	v_lshl_add_u64 v[60:61], s[2:3], 0, v[56:57]
	s_cmp_eq_u32 s28, 32
	s_cbranch_scc1 .Lxbskip_5
	global_store_dwordx4 v[60:61], v[52:55], off
.Lxbskip_5:
	global_store_dwordx4 v[58:59], v[40:43], off offset:512
	global_store_dwordx4 v[58:59], v[36:39], off offset:528
	v_or_b32_e32 v56, 0x100, v56
	v_cvt_pk_bf16_f32 v40, v40, v41
	v_cvt_pk_bf16_f32 v41, v42, v43
	v_cvt_pk_bf16_f32 v42, v36, v37
	s_waitcnt lgkmcnt(0)
	v_add_f32_e32 v36, v44, v45
	ds_bpermute_b32 v37, v221, v36
	v_cvt_pk_bf16_f32 v43, v38, v39
	v_lshl_add_u64 v[38:39], s[2:3], 0, v[56:57]
	s_cmp_eq_u32 s28, 32
	s_cbranch_scc1 .Lxbskip_4
	global_store_dwordx4 v[38:39], v[40:43], off
.Lxbskip_4:
	s_and_saveexec_b64 s[40:41], s[18:19]
	s_cbranch_execz .LBB0_604
	s_waitcnt lgkmcnt(0)
	v_add_f32_e32 v38, v36, v37
	v_lshlrev_b64 v[36:37], 6, v[128:129]
	v_lshl_add_u64 v[36:37], s[14:15], 0, v[36:37]
	v_lshl_add_u64 v[36:37], s[22:23], 2, v[36:37]
	s_lshl_b32 s8, s54, 2
	v_lshl_add_u64 v[36:37], v[36:37], 0, s[8:9]
	global_store_dword v[36:37], v38, off
; __device__ __forceinline__ unsigned pk2(float lo, float hi) { return pg8::cvt_pk_bf16(lo, hi); }
;     __device__ __forceinline__ void operator()(const pg8::f32x4 (&acc)[2][2][4][2], const pg8::Unit& u, int wr, int wc, int fr, int fq) const {
;     ...
;             for (int m = 0; m < 4; ++m) {
;                 const int row = row0 + ai * 128 + m * 16; float ss = 0.f;
; #pragma unroll
;                 for (int bj = 0; bj < 2; ++bj) {
;                     const size_t off = (size_t)row * DM + col0 + bj * 128;
;                     const f32x4 x0 = bv[m][bj][0] + acc[ai][bj][m][0] * alpha, x1 = bv[m][bj][1] + acc[ai][bj][m][1] * alpha;
;                     *(f32x4*)(out + off) = x0; *(f32x4*)(out + off + 4) = x1;
;                     u32x4 w; w.x = pk2(x0[0], x0[1]); w.y = pk2(x0[2], x0[3]); w.z = pk2(x1[0], x1[1]); w.w = pk2(x1[2], x1[3]);
;                     *(u32x4*)(xb + off) = w;
;                     ss += ((x0[0] * x0[0] + x0[1] * x0[1]) + (x0[2] * x0[2] + x0[3] * x0[3])) + ((x1[0] * x1[0] + x1[1] * x1[1]) + (x1[2] * x1[2] + x1[3] * x1[3]));
;                 }
;                 ss += __shfl_xor(ss, 16); ss += __shfl_xor(ss, 32);
;                 if (ssq && fq == 0) ssq[(size_t)row * 16 + u.pn * 4 + wc] = ss;
.LBB0_604:
	s_or_b64 exec, exec, s[40:41]
	s_waitcnt lgkmcnt(0)
	v_lshlrev_b64 v[36:37], 10, v[126:127]
	v_lshl_add_u64 v[40:41], v[36:37], 0, v[206:207]
	v_mov_b32_e32 v193, v192
	s_waitcnt vmcnt(18)
	v_pk_fma_f32 v[30:31], v[192:193], v[30:31], v[98:99]
	v_pk_fma_f32 v[28:29], v[194:195], v[28:29], v[96:97]
	v_pk_fma_f32 v[24:25], v[194:195], v[24:25], v[92:93]
	v_lshl_add_u64 v[42:43], v[40:41], 2, s[24:25]
	v_pk_fma_f32 v[26:27], v[192:193], v[26:27], v[94:95]
	global_store_dwordx4 v[42:43], v[28:31], off
	global_store_dwordx4 v[42:43], v[24:27], off offset:16
	v_cvt_pk_bf16_f32 v38, v24, v25
	s_waitcnt vmcnt(18)
	v_pk_fma_f32 v[22:23], v[192:193], v[22:23], v[86:87]
	v_mul_f32_e32 v25, v25, v25
	v_fmac_f32_e32 v25, v24, v24
	v_mul_f32_e32 v24, v27, v27
	v_fmac_f32_e32 v24, v26, v26
	v_pk_fma_f32 v[20:21], v[194:195], v[20:21], v[84:85]
	v_cvt_pk_bf16_f32 v39, v26, v27
	v_add_f32_e32 v24, v25, v24
	v_mul_f32_e32 v25, v21, v21
	v_mul_f32_e32 v26, v23, v23
	v_cvt_pk_bf16_f32 v36, v28, v29
	v_mul_f32_e32 v29, v29, v29
	v_pk_fma_f32 v[18:19], v[192:193], v[18:19], v[78:79]
	v_pk_fma_f32 v[16:17], v[194:195], v[16:17], v[76:77]
	v_fmac_f32_e32 v25, v20, v20
	v_fmac_f32_e32 v26, v22, v22
	v_fmac_f32_e32 v29, v28, v28
	v_mul_f32_e32 v28, v31, v31
	v_add_f32_e32 v25, v25, v26
	v_mul_f32_e32 v26, v17, v17
	v_mul_f32_e32 v27, v19, v19
	v_fmac_f32_e32 v28, v30, v30
	v_fmac_f32_e32 v26, v16, v16
	v_fmac_f32_e32 v27, v18, v18
	v_add_f32_e32 v28, v29, v28
	v_add_f32_e32 v26, v26, v27
	v_add_f32_e32 v24, v28, v24
	v_add_f32_e32 v25, v25, v26
	v_add_f32_e32 v24, v24, v25
	ds_bpermute_b32 v25, v222, v24
	v_lshlrev_b64 v[40:41], 1, v[40:41]
	v_cvt_pk_bf16_f32 v37, v30, v31
	v_lshl_add_u64 v[44:45], s[2:3], 0, v[40:41]
	s_cmp_eq_u32 s28, 32
	s_cbranch_scc1 .Lxbskip_3
	global_store_dwordx4 v[44:45], v[36:39], off
.Lxbskip_3:
	global_store_dwordx4 v[42:43], v[20:23], off offset:512
	global_store_dwordx4 v[42:43], v[16:19], off offset:528
	v_or_b32_e32 v40, 0x100, v40
	v_cvt_pk_bf16_f32 v20, v20, v21
	v_cvt_pk_bf16_f32 v21, v22, v23
	v_cvt_pk_bf16_f32 v22, v16, v17
	s_waitcnt lgkmcnt(0)
	v_add_f32_e32 v16, v24, v25
	ds_bpermute_b32 v17, v221, v16
	v_cvt_pk_bf16_f32 v23, v18, v19
	v_lshl_add_u64 v[18:19], s[2:3], 0, v[40:41]
	s_cmp_eq_u32 s28, 32
	s_cbranch_scc1 .Lxbskip_2
	global_store_dwordx4 v[18:19], v[20:23], off
.Lxbskip_2:
	s_and_saveexec_b64 s[40:41], s[18:19]
	s_cbranch_execz .LBB0_606
	s_waitcnt lgkmcnt(0)
	v_add_f32_e32 v18, v16, v17
	v_lshlrev_b64 v[16:17], 6, v[126:127]
	v_lshl_add_u64 v[16:17], s[14:15], 0, v[16:17]
	v_lshl_add_u64 v[16:17], s[22:23], 2, v[16:17]
	s_lshl_b32 s8, s54, 2
	v_lshl_add_u64 v[16:17], v[16:17], 0, s[8:9]
	global_store_dword v[16:17], v18, off
.LBB0_606:
	s_or_b64 exec, exec, s[40:41]
	s_waitcnt lgkmcnt(0)
	v_lshlrev_b64 v[16:17], 10, v[124:125]
	v_lshl_add_u64 v[20:21], v[16:17], 0, v[206:207]
	s_waitcnt vmcnt(20)
	v_pk_fma_f32 v[14:15], v[192:193], v[14:15], v[90:91]
	v_pk_fma_f32 v[12:13], v[194:195], v[12:13], v[88:89]
	v_pk_fma_f32 v[8:9], v[194:195], v[8:9], v[80:81]
	v_lshl_add_u64 v[22:23], v[20:21], 2, s[24:25]
	v_pk_fma_f32 v[10:11], v[192:193], v[10:11], v[82:83]
	global_store_dwordx4 v[22:23], v[12:15], off
	global_store_dwordx4 v[22:23], v[8:11], off offset:16
	v_cvt_pk_bf16_f32 v18, v8, v9
	s_waitcnt vmcnt(20)
	v_pk_fma_f32 v[6:7], v[192:193], v[6:7], v[74:75]
	v_mul_f32_e32 v9, v9, v9
	v_fmac_f32_e32 v9, v8, v8
	v_mul_f32_e32 v8, v11, v11
	v_fmac_f32_e32 v8, v10, v10
	v_pk_fma_f32 v[4:5], v[194:195], v[4:5], v[72:73]
	v_cvt_pk_bf16_f32 v19, v10, v11
	v_add_f32_e32 v8, v9, v8
	v_mul_f32_e32 v9, v5, v5
	v_mul_f32_e32 v10, v7, v7
	v_cvt_pk_bf16_f32 v16, v12, v13
	v_mul_f32_e32 v13, v13, v13
	v_pk_fma_f32 v[2:3], v[192:193], v[2:3], v[70:71]
	v_pk_fma_f32 v[0:1], v[194:195], v[0:1], v[68:69]
	v_fmac_f32_e32 v9, v4, v4
	v_fmac_f32_e32 v10, v6, v6
	v_fmac_f32_e32 v13, v12, v12
	v_mul_f32_e32 v12, v15, v15
	v_add_f32_e32 v9, v9, v10
	v_mul_f32_e32 v10, v1, v1
	v_mul_f32_e32 v11, v3, v3
	v_fmac_f32_e32 v12, v14, v14
	v_fmac_f32_e32 v10, v0, v0
	v_fmac_f32_e32 v11, v2, v2
	v_add_f32_e32 v12, v13, v12
	v_add_f32_e32 v10, v10, v11
	v_add_f32_e32 v8, v12, v8
	v_add_f32_e32 v9, v9, v10
	v_add_f32_e32 v8, v8, v9
	ds_bpermute_b32 v9, v222, v8
	v_lshlrev_b64 v[20:21], 1, v[20:21]
	v_cvt_pk_bf16_f32 v17, v14, v15
	v_lshl_add_u64 v[24:25], s[2:3], 0, v[20:21]
	s_cmp_eq_u32 s28, 32
	s_cbranch_scc1 .Lxbskip_1
	global_store_dwordx4 v[24:25], v[16:19], off
.Lxbskip_1:
	global_store_dwordx4 v[22:23], v[4:7], off offset:512
	global_store_dwordx4 v[22:23], v[0:3], off offset:528
	v_or_b32_e32 v20, 0x100, v20
	v_cvt_pk_bf16_f32 v4, v4, v5
	v_cvt_pk_bf16_f32 v5, v6, v7
	v_cvt_pk_bf16_f32 v6, v0, v1
	s_waitcnt lgkmcnt(0)
	v_add_f32_e32 v0, v8, v9
	ds_bpermute_b32 v1, v221, v0
	v_cvt_pk_bf16_f32 v7, v2, v3
	v_lshl_add_u64 v[2:3], s[2:3], 0, v[20:21]
	s_cmp_eq_u32 s28, 32
	s_cbranch_scc1 .Lxbskip_0
	global_store_dwordx4 v[2:3], v[4:7], off
.Lxbskip_0:
	s_and_saveexec_b64 s[40:41], s[18:19]
	s_cbranch_execz .LBB0_608
	s_waitcnt lgkmcnt(0)
	v_add_f32_e32 v2, v0, v1
	v_lshlrev_b64 v[0:1], 6, v[124:125]
	v_lshl_add_u64 v[0:1], s[14:15], 0, v[0:1]
	v_lshl_add_u64 v[0:1], s[22:23], 2, v[0:1]
	s_lshl_b32 s8, s54, 2
	v_lshl_add_u64 v[0:1], v[0:1], 0, s[8:9]
	global_store_dword v[0:1], v2, off
